# nt hint on last-use loads: the prefetched bf16 x/y rows of R2_0 and R1_1 and the attention Q fragments
# speedup vs baseline: 1.0002x; 1.0002x over previous
.LBB0_355:
	v_lshl_add_u64 v[8:9], s[48:49], 0, v[152:153]
	v_add_co_u32_e32 v12, vcc, s10, v8
	v_lshl_add_u64 v[10:11], s[50:51], 0, v[152:153]
	global_load_dwordx4 v[24:27], v152, s[48:49]
	global_load_dwordx4 v[28:31], v152, s[50:51]
	v_addc_co_u32_e32 v13, vcc, 0, v9, vcc
	global_load_dwordx4 v[32:35], v[12:13], off
	v_add_co_u32_e32 v12, vcc, s10, v10
	v_or_b32_e32 v14, s40, v187
	s_nop 0
	v_addc_co_u32_e32 v13, vcc, 0, v11, vcc
	global_load_dwordx4 v[36:39], v[12:13], off
	v_add_co_u32_e32 v40, vcc, s11, v8
	v_add_u32_e32 v12, s21, v186
	s_nop 0
	v_addc_co_u32_e32 v41, vcc, 0, v9, vcc
	v_mov_b32_e32 v15, v153
	v_add_co_u32_e32 v42, vcc, s11, v10
	v_lshl_add_u64 v[16:17], v[14:15], 1, v[154:155]
	v_add_u32_e32 v14, 16, v12
	v_addc_co_u32_e32 v43, vcc, 0, v11, vcc
	v_ashrrev_i32_e32 v13, 31, v12
	v_add_co_u32_e32 v44, vcc, s16, v8
	v_ashrrev_i32_e32 v15, 31, v14
	s_nop 0
	v_addc_co_u32_e32 v45, vcc, 0, v9, vcc
	v_lshlrev_b64 v[164:165], 11, v[12:13]
	v_lshlrev_b64 v[162:163], 11, v[14:15]
	v_add_co_u32_e32 v46, vcc, s16, v10
	v_lshl_add_u64 v[12:13], v[16:17], 0, v[164:165]
	v_lshl_add_u64 v[20:21], v[16:17], 0, v[162:163]
	v_addc_co_u32_e32 v47, vcc, 0, v11, vcc
	global_load_dwordx4 v[8:11], v[12:13], off nt
	s_nop 0
	global_load_dwordx4 v[12:15], v[12:13], off offset:64 nt
	s_nop 0
	global_load_dwordx4 v[16:19], v[20:21], off nt
	s_nop 0
	global_load_dwordx4 v[20:23], v[20:21], off offset:64 nt
	s_waitcnt vmcnt(7)
	ds_write_b128 v195, v[24:27]
	s_waitcnt vmcnt(6)
	ds_write_b128 v196, v[28:31] offset:16384
	s_waitcnt vmcnt(5)
	ds_write_b128 v195, v[32:35] offset:4096
	s_waitcnt vmcnt(4)
	ds_write_b128 v196, v[36:39] offset:25600
	s_waitcnt lgkmcnt(0)
	s_barrier
	global_load_dwordx4 v[24:27], v[40:41], off
	global_load_dwordx4 v[28:31], v[42:43], off
	global_load_dwordx4 v[32:35], v[44:45], off
	global_load_dwordx4 v[36:39], v[46:47], off
	ds_read_b128 v[40:43], v197
	ds_read_b128 v[44:47], v197 offset:2048
	ds_read_b128 v[56:59], v197 offset:4096
	ds_read_b128 v[60:63], v197 offset:6144
	ds_read_b128 v[64:67], v198
	ds_read_b128 v[88:91], v198 offset:2048
	v_mov_b32_e32 v200, 0
	s_waitcnt vmcnt(7) lgkmcnt(5)
	v_mfma_f32_16x16x32_bf16 v[48:51], v[40:43], v[8:11], v[4:7]
	s_cmp_eq_u64 exec, 0
	s_waitcnt vmcnt(5)
	v_mfma_f32_16x16x32_bf16 v[40:43], v[40:43], v[16:19], v[4:7]
	s_waitcnt lgkmcnt(4)
	v_mfma_f32_16x16x32_bf16 v[52:55], v[44:47], v[8:11], v[4:7]
	v_mfma_f32_16x16x32_bf16 v[44:47], v[44:47], v[16:19], v[4:7]
	s_waitcnt lgkmcnt(1)
	v_mfma_f32_16x16x32_bf16 v[76:79], v[64:67], v[12:15], v[48:51]
	s_waitcnt vmcnt(4)
	v_mfma_f32_16x16x32_bf16 v[68:71], v[64:67], v[20:23], v[40:43]
	s_waitcnt lgkmcnt(0)
	v_mfma_f32_16x16x32_bf16 v[64:67], v[88:91], v[20:23], v[44:47]
	s_nop 0
	ds_read_b128 v[40:43], v198 offset:4096
	s_nop 0
	ds_read_b128 v[44:47], v198 offset:6144
	v_mfma_f32_16x16x32_bf16 v[80:83], v[56:59], v[8:11], v[4:7]
	v_mfma_f32_16x16x32_bf16 v[56:59], v[56:59], v[16:19], v[4:7]
	v_mfma_f32_16x16x32_bf16 v[84:87], v[60:63], v[8:11], v[4:7]
	v_mfma_f32_16x16x32_bf16 v[60:63], v[60:63], v[16:19], v[4:7]
	v_mfma_f32_16x16x32_bf16 v[72:75], v[88:91], v[12:15], v[52:55]
	s_waitcnt lgkmcnt(1)
	v_mfma_f32_16x16x32_bf16 v[52:55], v[40:43], v[12:15], v[80:83]
	v_mfma_f32_16x16x32_bf16 v[40:43], v[40:43], v[20:23], v[56:59]
	s_waitcnt lgkmcnt(0)
	v_mfma_f32_16x16x32_bf16 v[48:51], v[44:47], v[12:15], v[84:87]
	v_mfma_f32_16x16x32_bf16 v[44:47], v[44:47], v[20:23], v[60:63]
	s_cbranch_scc1 .LBB0_358
	v_max3_f32 v56, v76, s17, v77
	v_max3_f32 v56, v56, v78, v79
	v_max3_f32 v56, v56, v72, v73
	v_max3_f32 v56, v56, v74, v75
	v_max3_f32 v56, v56, v52, v53
	v_max3_f32 v56, v56, v54, v55
	v_max3_f32 v56, v56, v48, v49
	v_max3_f32 v56, v56, v50, v51
	v_mov_b32_e32 v57, v56
	s_nop 1
	v_permlane16_swap_b32_e32 v56, v57
	v_max_f32_e32 v57, v57, v57
	v_max_f32_e32 v56, v56, v56
	v_max_f32_e32 v56, v56, v57
	v_mov_b32_e32 v57, v56
	s_nop 1
	v_permlane32_swap_b32_e32 v56, v57
	v_max3_f32 v57, v56, v57, s18
	v_exp_f32_e64 v56, -v57
	v_add_f32_e32 v201, 0, v57
	v_sub_f32_e32 v79, v79, v57
	v_sub_f32_e32 v78, v78, v57
	v_mul_f32_e32 v56, 0, v56
	v_sub_f32_e32 v77, v77, v57
	v_sub_f32_e32 v76, v76, v57
	v_sub_f32_e32 v75, v75, v57
	v_sub_f32_e32 v74, v74, v57
	v_sub_f32_e32 v73, v73, v57
	v_sub_f32_e32 v72, v72, v57
	v_sub_f32_e32 v55, v55, v57
	v_sub_f32_e32 v54, v54, v57
	v_sub_f32_e32 v53, v53, v57
	v_sub_f32_e32 v52, v52, v57
	v_sub_f32_e32 v51, v51, v57
	v_sub_f32_e32 v50, v50, v57
	v_sub_f32_e32 v49, v49, v57
	v_sub_f32_e32 v48, v48, v57
	s_cmp_eq_u64 exec, 0
	s_cbranch_scc1 .LBB0_359

.LBB0_863:
	v_lshl_add_u32 v0, v105, 2, v103
	v_ashrrev_i32_e32 v0, 11, v0
	v_add_u32_e32 v0, 1, v0
	v_cmp_lt_i32_e32 vcc, s2, v105
	s_mov_b32 s5, 0
	s_nop 0
	v_cndmask_b32_e32 v2, 0, v0, vcc
	v_mul_hi_i32_i24_e32 v1, 0x6000, v2
	v_mul_i32_i24_e32 v0, 0x6000, v2
	v_lshl_add_u64 v[0:1], s[56:57], 0, v[0:1]
	v_add_u32_e32 v2, 3, v2
	v_mul_hi_i32_i24_e32 v3, 0x6000, v2
	v_mul_i32_i24_e32 v2, 0x6000, v2
	v_lshl_add_u64 v[40:41], v[0:1], 0, s[12:13]
	v_lshl_add_u64 v[24:25], s[56:57], 0, v[2:3]
	v_lshl_add_u64 v[12:13], v[40:41], 0, v[64:65]
	v_lshl_add_u64 v[48:49], v[24:25], 0, s[14:15]
	global_load_dwordx4 v[0:3], v[72:73], off offset:16
	global_load_dwordx4 v[4:7], v[72:73], off
	global_load_dwordx4 v[8:11], v[12:13], off offset:16
	s_nop 0
	global_load_dwordx4 v[12:15], v[12:13], off
	s_nop 0
	global_load_dwordx4 v[16:19], v[74:75], off offset:16
	global_load_dwordx4 v[20:23], v[74:75], off
	v_lshl_add_u64 v[60:61], v[24:25], 0, v[64:65]
	v_lshl_add_u64 v[32:33], v[48:49], 0, v[64:65]
	v_lshl_add_u64 v[44:45], v[40:41], 0, v[80:81]
	global_load_dwordx4 v[24:27], v[60:61], off offset:16
	global_load_dwordx4 v[28:31], v[60:61], off
	global_load_dwordx4 v[88:91], v[32:33], off offset:16
	global_load_dwordx4 v[84:87], v[32:33], off
	s_nop 0
	global_load_dwordx4 v[32:35], v[76:77], off offset:16
	global_load_dwordx4 v[36:39], v[76:77], off
	global_load_dwordx4 v[40:43], v[44:45], off offset:16
	s_nop 0
	global_load_dwordx4 v[44:47], v[44:45], off
	v_lshl_add_u64 v[48:49], v[48:49], 0, v[80:81]
	global_load_dwordx4 v[96:99], v[48:49], off offset:16
	global_load_dwordx4 v[92:95], v[48:49], off
	s_nop 0
	global_load_dwordx4 v[48:51], v[78:79], off offset:16
	global_load_dwordx4 v[52:55], v[78:79], off
	global_load_dwordx4 v[56:59], v[60:61], off offset:2064
	s_nop 0
	global_load_dwordx4 v[60:63], v[60:61], off offset:2048
	s_waitcnt vmcnt(11)
	v_pk_add_f32 v[88:89], v[88:89], 1.0 op_sel_hi:[1,0]
	s_waitcnt vmcnt(10)
	v_pk_add_f32 v[82:83], v[86:87], 1.0 op_sel_hi:[1,0]
	v_pk_add_f32 v[84:85], v[84:85], 1.0 op_sel_hi:[1,0]
	v_pk_add_f32 v[86:87], v[90:91], 1.0 op_sel_hi:[1,0]
	s_waitcnt vmcnt(4)
	v_pk_add_f32 v[90:91], v[94:95], 1.0 op_sel_hi:[1,0]
	v_pk_add_f32 v[92:93], v[92:93], 1.0 op_sel_hi:[1,0]
	v_pk_add_f32 v[94:95], v[98:99], 1.0 op_sel_hi:[1,0]
	v_pk_add_f32 v[96:97], v[96:97], 1.0 op_sel_hi:[1,0]
	v_mov_b32_e32 v98, v102
	v_ashrrev_i32_e32 v99, 31, v102
	s_mov_b64 s[60:61], 0x1000
	v_lshlrev_b64 v[98:99], 11, v[98:99]
	v_lshl_add_u64 v[122:123], v[66:67], 0, v[98:99]
	v_lshl_add_u64 v[118:119], v[68:69], 0, v[98:99]
	global_load_dwordx4 v[224:227], v[122:123], off nt
	global_load_dwordx4 v[228:231], v[122:123], off offset:1024 nt
	global_load_dwordx4 v[232:235], v[118:119], off nt
	global_load_dwordx4 v[236:239], v[118:119], off offset:1024 nt
	global_load_dwordx4 v[240:243], v[122:123], off offset:2048 nt
	global_load_dwordx4 v[244:247], v[122:123], off offset:3072 nt
	global_load_dwordx4 v[248:251], v[118:119], off offset:2048 nt
	global_load_dwordx4 v[252:255], v[118:119], off offset:3072 nt
	v_lshl_add_u64 v[122:123], v[122:123], 0, s[60:61]
	v_lshl_add_u64 v[118:119], v[118:119], 0, s[60:61]
	global_load_dwordx4 v[188:191], v[122:123], off nt
	global_load_dwordx4 v[192:195], v[122:123], off offset:1024 nt
	global_load_dwordx4 v[196:199], v[118:119], off nt
	global_load_dwordx4 v[200:203], v[118:119], off offset:1024 nt
	global_load_dwordx4 v[204:207], v[122:123], off offset:2048 nt
	global_load_dwordx4 v[208:211], v[122:123], off offset:3072 nt
	global_load_dwordx4 v[212:215], v[118:119], off offset:2048 nt
	global_load_dwordx4 v[220:223], v[118:119], off offset:3072 nt

.LBB0_1096:
	s_lshl_b32 s9, s9, 2
	s_lshl_b32 s12, s12, 1
	s_add_i32 s9, s9, s12
	s_sub_i32 s7, s7, s18
	v_or_b32_e32 v12, s9, v183
	v_add_u32_e32 v4, s8, v135
	s_add_i32 s21, s20, s7
	s_lshl_b64 s[8:9], s[18:19], 15
	s_add_u32 s7, s26, s8
	s_addc_u32 s14, s27, s9
	v_lshlrev_b32_e32 v128, 6, v12
	s_and_b64 s[12:13], s[24:25], exec
	v_readlane_b32 s80, v219, 0
	v_ashrrev_i32_e32 v129, 31, v128
	v_lshlrev_b64 v[130:131], 11, v[4:5]
	v_add_u32_e32 v4, 16, v4
	s_cselect_b32 s13, s41, s14
	s_cselect_b32 s12, s40, s7
	s_add_u32 s7, s36, s8
	v_ashrrev_i32_e32 v13, 31, v12
	v_readlane_b32 s81, v219, 1
	v_lshl_add_u64 v[20:21], v[128:129], 1, v[124:125]
	s_addc_u32 s14, s37, s9
	v_lshlrev_b64 v[132:133], 11, v[4:5]
	v_lshl_add_u64 v[6:7], v[12:13], 2, s[80:81]
	v_lshl_add_u64 v[16:17], v[20:21], 0, v[130:131]
	s_and_b64 s[8:9], s[24:25], exec
	v_lshl_add_u64 v[24:25], v[20:21], 0, v[132:133]
	global_load_dword v6, v[6:7], off
	s_nop 0
	global_load_dwordx4 v[12:15], v[16:17], off nt
	s_nop 0
	global_load_dwordx4 v[16:19], v[16:17], off offset:64 nt
	s_cselect_b32 s9, s39, s14
	s_cselect_b32 s8, s38, s7
	global_load_dwordx4 v[32:35], v141, s[12:13]
	global_load_dwordx4 v[36:39], v141, s[8:9]
	global_load_dwordx4 v[20:23], v[24:25], off nt
	s_nop 0
	global_load_dwordx4 v[24:27], v[24:25], off offset:64 nt
	s_cmp_lt_i32 s21, 1
	v_readlane_b32 s82, v219, 2
	v_readlane_b32 s83, v219, 3
	v_readlane_b32 s84, v219, 4
	v_readlane_b32 s85, v219, 5
	v_readlane_b32 s86, v219, 6
	v_readlane_b32 s87, v219, 7
	s_waitcnt vmcnt(3)
	ds_write_b128 v142, v[32:35]
	s_waitcnt vmcnt(2)
	ds_write_b128 v143, v[36:39] offset:8192
	s_waitcnt lgkmcnt(0)
	s_barrier
	s_cbranch_scc1 .LBB0_1089
	v_lshl_or_b32 v4, s18, 6, v146
	s_lshl_b32 s8, s20, 6
	v_mul_f32_e32 v149, 0x3fb8aa3b, v6
	s_lshr_b32 s74, s6, 6
	v_sub_u32_e32 v4, s8, v4
	v_mov_b32_e32 v6, v5
	v_mov_b32_e32 v7, v5
	s_sub_i32 s73, s18, s20
	s_add_i32 s7, s74, s20
	v_add3_u32 v150, v135, s6, v4
	v_mov_b32_e32 v4, v5
	v_mov_b64_e32 v[30:31], v[6:7]
	v_mov_b64_e32 v[42:43], v[6:7]
	v_mov_b64_e32 v[46:47], v[6:7]
	v_mov_b64_e32 v[58:59], v[6:7]
	v_mov_b64_e32 v[50:51], v[6:7]
	v_mov_b64_e32 v[62:63], v[6:7]
	v_mov_b64_e32 v[54:55], v[6:7]
	v_mov_b64_e32 v[66:67], v[6:7]
	v_mov_b64_e32 v[70:71], v[2:3]
	v_mov_b64_e32 v[74:75], v[2:3]
	s_ashr_i32 s75, s73, 31
	s_sub_i32 s18, s18, s7
	s_mov_b64 s[6:7], 0
	v_mov_b64_e32 v[28:29], v[4:5]
	v_mov_b64_e32 v[40:41], v[4:5]
	v_mov_b64_e32 v[44:45], v[4:5]
	v_mov_b64_e32 v[56:57], v[4:5]
	v_mov_b64_e32 v[48:49], v[4:5]
	v_mov_b64_e32 v[60:61], v[4:5]
	v_mov_b64_e32 v[52:53], v[4:5]
	v_mov_b64_e32 v[64:65], v[4:5]
	v_mov_b32_e32 v7, v149
	v_mov_b64_e32 v[68:69], v[0:1]
	v_mov_b64_e32 v[72:73], v[0:1]

.LBB0_1290:
	v_lshl_add_u32 v0, v105, 2, v103
	v_ashrrev_i32_e32 v0, 11, v0
	v_add_u32_e32 v0, 4, v0
	v_cmp_lt_i32_e32 vcc, s2, v105
	s_mov_b32 s5, 0
	s_nop 0
	v_cndmask_b32_e32 v0, 3, v0, vcc
	v_mul_hi_i32_i24_e32 v1, 0x6000, v0
	v_mul_i32_i24_e32 v0, 0x6000, v0
	v_lshl_add_u64 v[0:1], s[56:57], 0, v[0:1]
	v_lshl_add_u64 v[40:41], v[0:1], 0, s[12:13]
	v_lshl_add_u64 v[24:25], v[40:41], 0, v[64:65]
	v_lshl_add_u64 v[56:57], v[0:1], 0, s[14:15]
	v_lshl_add_u64 v[48:49], v[0:1], 0, s[18:19]
	global_load_dwordx4 v[0:3], v[72:73], off offset:16
	global_load_dwordx4 v[4:7], v[72:73], off
	global_load_dwordx4 v[8:11], v[24:25], off offset:16
	global_load_dwordx4 v[12:15], v[24:25], off
	global_load_dwordx4 v[16:19], v[74:75], off offset:16
	global_load_dwordx4 v[20:23], v[74:75], off
	v_lshl_add_u64 v[32:33], v[56:57], 0, v[64:65]
	v_lshl_add_u64 v[42:43], v[48:49], 0, v[64:65]
	v_lshl_add_u64 v[50:51], v[40:41], 0, v[80:81]
	v_lshl_add_u64 v[58:59], v[48:49], 0, v[80:81]
	v_lshl_add_u64 v[82:83], v[56:57], 0, v[80:81]
	global_load_dwordx4 v[24:27], v[32:33], off offset:16
	global_load_dwordx4 v[28:31], v[32:33], off
	global_load_dwordx4 v[88:91], v[42:43], off offset:16
	global_load_dwordx4 v[84:87], v[42:43], off
	s_nop 0
	global_load_dwordx4 v[32:35], v[76:77], off offset:16
	global_load_dwordx4 v[36:39], v[76:77], off
	global_load_dwordx4 v[40:43], v[50:51], off offset:16
	global_load_dwordx4 v[44:47], v[50:51], off
	global_load_dwordx4 v[96:99], v[58:59], off offset:16
	global_load_dwordx4 v[92:95], v[58:59], off
	s_nop 0
	global_load_dwordx4 v[48:51], v[78:79], off offset:16
	global_load_dwordx4 v[52:55], v[78:79], off
	global_load_dwordx4 v[56:59], v[82:83], off offset:16
	global_load_dwordx4 v[60:63], v[82:83], off
	s_waitcnt vmcnt(11)
	v_pk_add_f32 v[88:89], v[88:89], 1.0 op_sel_hi:[1,0]
	s_waitcnt vmcnt(10)
	v_pk_add_f32 v[82:83], v[86:87], 1.0 op_sel_hi:[1,0]
	v_pk_add_f32 v[84:85], v[84:85], 1.0 op_sel_hi:[1,0]
	v_pk_add_f32 v[86:87], v[90:91], 1.0 op_sel_hi:[1,0]
	s_waitcnt vmcnt(4)
	v_pk_add_f32 v[90:91], v[94:95], 1.0 op_sel_hi:[1,0]
	v_pk_add_f32 v[92:93], v[92:93], 1.0 op_sel_hi:[1,0]
	v_pk_add_f32 v[94:95], v[98:99], 1.0 op_sel_hi:[1,0]
	v_pk_add_f32 v[96:97], v[96:97], 1.0 op_sel_hi:[1,0]
	v_mov_b32_e32 v98, v102
	v_ashrrev_i32_e32 v99, 31, v102
	s_mov_b64 s[60:61], 0x1000
	v_lshlrev_b64 v[98:99], 11, v[98:99]
	v_lshl_add_u64 v[122:123], v[68:69], 0, v[98:99]
	v_lshl_add_u64 v[118:119], v[66:67], 0, v[98:99]
	global_load_dwordx4 v[224:227], v[122:123], off nt
	global_load_dwordx4 v[228:231], v[122:123], off offset:1024 nt
	global_load_dwordx4 v[232:235], v[118:119], off nt
	global_load_dwordx4 v[236:239], v[118:119], off offset:1024 nt
	global_load_dwordx4 v[240:243], v[122:123], off offset:2048 nt
	global_load_dwordx4 v[244:247], v[122:123], off offset:3072 nt
	global_load_dwordx4 v[248:251], v[118:119], off offset:2048 nt
	global_load_dwordx4 v[252:255], v[118:119], off offset:3072 nt
	v_lshl_add_u64 v[122:123], v[122:123], 0, s[60:61]
	v_lshl_add_u64 v[118:119], v[118:119], 0, s[60:61]
	global_load_dwordx4 v[188:191], v[122:123], off nt
	global_load_dwordx4 v[192:195], v[122:123], off offset:1024 nt
	global_load_dwordx4 v[196:199], v[118:119], off nt
	global_load_dwordx4 v[200:203], v[118:119], off offset:1024 nt
	global_load_dwordx4 v[204:207], v[122:123], off offset:2048 nt
	global_load_dwordx4 v[208:211], v[122:123], off offset:3072 nt
	global_load_dwordx4 v[212:215], v[118:119], off offset:2048 nt
	global_load_dwordx4 v[220:223], v[118:119], off offset:3072 nt
